# coalesced K/V tile loaders (each wave-load covers 8 whole 128-B rows) in SB, SWA and MoBA
# speedup vs baseline: 1.0312x; 1.0179x over previous
; #define LAS __attribute__((address_space(3)))
; DI void coop_load_tiles(const bf16_t* kbase, int vdelta, int t_hi, int nt, LAS unsigned char* lds, int wid, int lane) {
; #pragma unroll 1
;     for (int s0 = 0; s0 < nt; s0 += 4) {
;         u32x4 kr[4], vr[4];
; #pragma unroll
;         for (int s = 0; s < 4; ++s) if (s0 + s < nt) { const bf16_t* src = kbase + (size_t)((t_hi - s0 - s) * 64 + lane) * PITCH + 8 * wid; kr[s] = *(const u32x4*)src; vr[s] = *(const u32x4*)(src + vdelta); }
; #pragma unroll
;         for (int s = 0; s < 4; ++s) if (s0 + s < nt) { *(LAS u32x4*)(lds + (s0 + s) * 16384 + wid * 1024 + lane * 16) = kr[s];
;             *(LAS u32x4*)(lds + (s0 + s) * 16384 + 8192 + (wid >> 2) * 4096 + lane * 64 + (wid & 3) * 16) = vr[s]; }
;     }
.LBB0_331:
	v_readlane_b32 s6, v250, 7
	v_readlane_b32 s7, v250, 8
	s_andn2_b64 vcc, exec, s[6:7]
	s_cbranch_vccnz .LBB0_358
	s_lshl_b32 s8, s20, 10
	s_lshl_b32 s10, s20, 4
	s_and_b32 s9, s8, 0xfffff000
	s_and_b32 s10, s10, 48
	s_add_i32 s8, s8, 0
	v_lshlrev_b32_e32 v7, 4, v99
	v_and_b32_e32 v83, 31, v99
	v_lshlrev_b32_e32 v4, 1, v106
	v_lshlrev_b32_e32 v5, 3, v106
	s_add_i32 s10, s10, 0
	v_lshl_add_u32 v93, v106, 4, s8
	v_lshlrev_b32_e32 v6, 3, v99
	v_and_b32_e32 v7, 0xc0, v7
	s_movk_i32 s8, 0x100
	v_lshrrev_b32_e32 v2, 5, v106
	s_lshl_b32 s6, s20, 3
	v_lshlrev_b32_e32 v3, 4, v83
	v_and_b32_e32 v4, 32, v4
	v_and_b32_e32 v5, 24, v5
	s_add_i32 s9, s10, s9
	v_and_or_b32 v6, v6, s8, v7
	v_lshlrev_b32_e32 v0, 3, v2
	s_ashr_i32 s7, s6, 31
	v_lshlrev_b32_e32 v82, 2, v2
	s_addk_i32 s9, 0x2000
	v_or3_b32 v4, v6, v4, v5
	v_lshl_or_b32 v2, v2, 10, v3
	s_lshl_b32 s16, s20, 5
	v_cmp_eq_u32_e64 s[40:41], 0, v99
	v_cmp_gt_u32_e64 s[42:43], 32, v106
	v_cmp_ne_u32_e64 s[44:45], 0, v106
	v_lshl_add_u32 v92, v106, 6, s9
	v_or_b32_e32 v94, 0xffffff40, v106
	v_add_u32_e32 v95, 0, v4
	v_add_u32_e32 v96, 0, v2
	v_lshlrev_b32_e32 v0, 1, v0
	s_lshl_b64 s[46:47], s[6:7], 1
	s_mov_b32 s17, s2
	v_and_b32_e32 v146, 7, v106
	v_lshl_add_u32 v146, s20, 3, v146
	v_lshrrev_b32_e32 v147, 3, v106
	v_add_u32_e32 v94, 0xffffff40, v146
	v_lshlrev_b32_e32 v93, 4, v146
	v_lshl_add_u32 v93, v147, 10, v93
	v_lshlrev_b32_e32 v92, 6, v146
	v_and_b32_e32 v148, 3, v147
	v_lshl_add_u32 v92, v148, 4, v92
	v_lshrrev_b32_e32 v148, 2, v147
	v_lshl_add_u32 v92, v148, 12, v92
	v_add_u32_e32 v92, 0x2000, v92
	v_lshlrev_b32_e32 v146, 4, v147
	v_mov_b32_e32 v147, 0
	s_branch .LBB0_334

; DI void sb_wg_unit(bf16_t* act, int b, int hh, int Qb, LAS unsigned char* lds, volatile LAS unsigned* ctl, int tid, int wid, int lane) {
;     const int r = lane & 31, h = lane >> 5;
;     const int Q = Qb * 256, q0 = Q + 32 * wid, qpos = q0 + r;
;     const size_t rowq = (size_t)b * SEQ + qpos;
;     bf16x8 qf[4]; load_q(qf, act + rowq * PITCH + C_QA + hh * 64, h);
;     f32x16 o0, o1;
; #pragma unroll
;     for (int i = 0; i < 16; ++i) { o0[i] = 0.f; o1[i] = 0.f; }
;     float C = 1.f;
;     const bf16_t* kgb = act + (size_t)b * SEQ * PITCH + C_KA + hh * 64;
;     int t = q0 >> 6;
;     bool done = false;
;     int t_top = (Q >> 6) + 3;
.LBB0_334:
	s_and_b32 s98, s17, 7
	s_lshl_b32 s98, s98, 5
	s_bfe_u32 s99, s17, 0x50003
	s_or_b32 s98, s98, s99
	s_andn2_b32 s99, s17, 0xff
	s_or_b32 s98, s98, s99
	s_and_b32 s10, s98, 31
	s_lshl_b32 s21, s10, 8
	s_ashr_i32 s6, s98, 8
	s_add_i32 s21, s21, s16
	v_or_b32_e32 v86, s21, v83
	s_ashr_i32 s7, s6, 31
	s_lshl_b64 s[8:9], s[6:7], 13
	v_ashrrev_i32_e32 v87, 31, v86
	v_lshl_add_u64 v[2:3], s[8:9], 0, v[86:87]
	v_mov_b64_e32 v[4:5], s[76:77]
	v_mad_u64_u32 v[4:5], s[8:9], v2, s31, v[4:5]
	s_lshl_b32 s7, s98, 2
	v_mad_i32_i24 v5, v3, s31, v5
	s_and_b32 s38, s7, 0x380
	v_lshl_add_u64 v[88:89], v[4:5], 0, s[38:39]
	v_lshl_add_u64 v[84:85], v[88:89], 0, v[0:1]
	global_load_dwordx4 v[66:69], v[84:85], off
	global_load_dwordx4 v[70:73], v[84:85], off offset:32
	global_load_dwordx4 v[74:77], v[84:85], off offset:64
	global_load_dwordx4 v[78:81], v[84:85], off offset:96
	s_mul_hi_i32 s7, s6, 0x6400000
	s_mul_i32 s6, s6, 0x6400000
	s_add_u32 s6, s76, s6
	s_addc_u32 s7, s77, s7
	s_add_u32 s6, s6, s38
	s_addc_u32 s7, s7, 0
	s_lshl_b32 s8, s10, 2
	s_ashr_i32 s24, s21, 6
	s_or_b32 s25, s8, 3
	v_mov_b32_e32 v18, v1
	v_mov_b32_e32 v19, v1
	v_mov_b32_e32 v20, v1
	v_mov_b32_e32 v21, v1
	v_mov_b32_e32 v22, v1
	v_mov_b32_e32 v23, v1
	v_mov_b32_e32 v24, v1
	v_mov_b32_e32 v25, v1
	v_mov_b32_e32 v26, v1
	v_mov_b32_e32 v27, v1
	v_mov_b32_e32 v28, v1
	v_mov_b32_e32 v29, v1
	v_mov_b32_e32 v30, v1
	v_mov_b32_e32 v31, v1
	v_mov_b32_e32 v32, v1
	v_mov_b32_e32 v33, v1
	s_waitcnt lgkmcnt(0)
	v_mov_b64_e32 v[2:3], v[18:19]
	v_mov_b32_e32 v91, 1.0
	s_mov_b64 s[8:9], 0
	v_mov_b64_e32 v[4:5], v[20:21]
	v_mov_b64_e32 v[6:7], v[22:23]
	v_mov_b64_e32 v[8:9], v[24:25]
	v_mov_b64_e32 v[10:11], v[26:27]
	v_mov_b64_e32 v[12:13], v[28:29]
	v_mov_b64_e32 v[14:15], v[30:31]
	v_mov_b64_e32 v[16:17], v[32:33]
	s_branch .LBB0_336

; #define LAS __attribute__((address_space(3)))
; DI void coop_load_tiles(const bf16_t* kbase, int vdelta, int t_hi, int nt, LAS unsigned char* lds, int wid, int lane) {
; #pragma unroll 1
;     for (int s0 = 0; s0 < nt; s0 += 4) {
;         u32x4 kr[4], vr[4];
; #pragma unroll
;         for (int s = 0; s < 4; ++s) if (s0 + s < nt) { const bf16_t* src = kbase + (size_t)((t_hi - s0 - s) * 64 + lane) * PITCH + 8 * wid; kr[s] = *(const u32x4*)src; vr[s] = *(const u32x4*)(src + vdelta); }
; #pragma unroll
;         for (int s = 0; s < 4; ++s) if (s0 + s < nt) { *(LAS u32x4*)(lds + (s0 + s) * 16384 + wid * 1024 + lane * 16) = kr[s];
;             *(LAS u32x4*)(lds + (s0 + s) * 16384 + 8192 + (wid >> 2) * 4096 + lane * 64 + (wid & 3) * 16) = vr[s]; }
;     }
.LBB0_341:
	v_add_u32_e32 v60, 0xc0, v87
	v_lshl_add_u64 v[58:59], s[6:7], 0, v[146:147]
	v_mad_i64_i32 v[58:59], s[10:11], v60, s31, v[58:59]
	global_load_dwordx4 v[62:65], v[58:59], off offset:1024
	s_nop 0
	global_load_dwordx4 v[58:61], v[58:59], off offset:2048
	s_cmp_lt_i32 s12, s26
	s_cselect_b64 s[10:11], -1, 0
	s_cmp_ge_i32 s12, s26
	s_cbranch_scc1 .LBB0_343
	v_add_u32_e32 v36, 0x80, v87
	v_lshl_add_u64 v[34:35], s[6:7], 0, v[146:147]
	v_mad_i64_i32 v[46:47], s[14:15], v36, s31, v[34:35]
	global_load_dwordx4 v[34:37], v[46:47], off offset:1024
	s_nop 0
	global_load_dwordx4 v[46:49], v[46:47], off offset:2048
.LBB0_343:
	s_add_i32 s27, s12, 2
	s_cmp_le_i32 s27, s26
	s_cselect_b64 s[12:13], -1, 0
	s_cmp_gt_i32 s27, s26
	s_cbranch_scc1 .LBB0_345
	v_add_u32_e32 v40, 64, v87
	v_lshl_add_u64 v[38:39], s[6:7], 0, v[146:147]
	v_mad_i64_i32 v[50:51], s[14:15], v40, s31, v[38:39]
	global_load_dwordx4 v[38:41], v[50:51], off offset:1024
	s_nop 0
	global_load_dwordx4 v[50:53], v[50:51], off offset:2048

; #define LAS __attribute__((address_space(3)))
; DI void coop_load_tiles(const bf16_t* kbase, int vdelta, int t_hi, int nt, LAS unsigned char* lds, int wid, int lane) {
; #pragma unroll 1
;     for (int s0 = 0; s0 < nt; s0 += 4) {
;         u32x4 kr[4], vr[4];
; #pragma unroll
;         for (int s = 0; s < 4; ++s) if (s0 + s < nt) { const bf16_t* src = kbase + (size_t)((t_hi - s0 - s) * 64 + lane) * PITCH + 8 * wid; kr[s] = *(const u32x4*)src; vr[s] = *(const u32x4*)(src + vdelta); }
; #pragma unroll
;         for (int s = 0; s < 4; ++s) if (s0 + s < nt) { *(LAS u32x4*)(lds + (s0 + s) * 16384 + wid * 1024 + lane * 16) = kr[s];
;             *(LAS u32x4*)(lds + (s0 + s) * 16384 + 8192 + (wid >> 2) * 4096 + lane * 64 + (wid & 3) * 16) = vr[s]; }
;     }
.LBB0_349:
	s_waitcnt vmcnt(3)
	v_lshl_add_u64 v[42:43], s[6:7], 0, v[146:147]
	s_waitcnt vmcnt(2)
	v_mad_i64_i32 v[54:55], s[28:29], v87, s31, v[42:43]
	global_load_dwordx4 v[42:45], v[54:55], off offset:1024
	s_nop 0
	global_load_dwordx4 v[54:57], v[54:55], off offset:2048
	s_andn2_b64 vcc, exec, s[10:11]
	s_waitcnt vmcnt(3)
	ds_write_b128 v90, v[62:65]
	s_waitcnt vmcnt(2)
	ds_write_b128 v97, v[58:61]
	s_cbranch_vccnz .LBB0_347

; #define LAS __attribute__((address_space(3)))
; DI void coop_load_tiles(const bf16_t* kbase, int vdelta, int t_hi, int nt, LAS unsigned char* lds, int wid, int lane) {
; #pragma unroll 1
;     for (int s0 = 0; s0 < nt; s0 += 4) {
;         u32x4 kr[4], vr[4];
; #pragma unroll
;         for (int s = 0; s < 4; ++s) if (s0 + s < nt) { const bf16_t* src = kbase + (size_t)((t_hi - s0 - s) * 64 + lane) * PITCH + 8 * wid; kr[s] = *(const u32x4*)src; vr[s] = *(const u32x4*)(src + vdelta); }
; #pragma unroll
;         for (int s = 0; s < 4; ++s) if (s0 + s < nt) { *(LAS u32x4*)(lds + (s0 + s) * 16384 + wid * 1024 + lane * 16) = kr[s];
;             *(LAS u32x4*)(lds + (s0 + s) * 16384 + 8192 + (wid >> 2) * 4096 + lane * 64 + (wid & 3) * 16) = vr[s]; }
;     }
; DI void swa_wg_unit(bf16_t* act, int b, int hk, int Qb, const float* sinks_l, LAS const float* tabS, LAS unsigned char* lds, int wid, int lane) {
;     const int r = lane & 31, h = lane >> 5;
;     const int Q = Qb * 256, q0 = Q + 32 * wid, qpos = q0 + r;
;     const size_t rowq = (size_t)b * SEQ + qpos;
;     const int t_hi = (Q >> 6) + 3, t_lo = (Q >= 128) ? ((Q - 128) >> 6) : 0;
;     __syncthreads();
;     coop_load_tiles(act + (size_t)b * SEQ * PITCH + C_KC + hk * 64, C_VC - C_KC, t_hi, t_hi - t_lo + 1, lds, wid, lane);
;     __syncthreads();
;     const int tlo = (q0 >= 127) ? ((q0 - 127) >> 6) : 0;
.LBB0_358:
	v_readlane_b32 s6, v250, 9
	v_readlane_b32 s7, v250, 10
	s_andn2_b64 vcc, exec, s[6:7]
	s_cbranch_vccnz .LBB0_383
	v_readlane_b32 s6, v249, 6
	v_readlane_b32 s7, v249, 7
	s_lshl_b32 s38, s6, 3
	v_readlane_b32 s8, v250, 47
	s_lshl_b64 s[6:7], s[38:39], 2
	v_readlane_b32 s10, v250, 49
	v_readlane_b32 s11, v250, 50
	s_add_u32 s16, s10, s6
	v_readlane_b32 s9, v250, 48
	s_addc_u32 s17, s11, s7
	v_and_b32_e32 v107, 31, v99
	v_lshrrev_b32_e32 v3, 5, v106
	s_lshl_b32 s21, s20, 5
	s_lshl_b32 s8, s20, 10
	s_lshl_b32 s10, s20, 4
	s_and_b32 s9, s8, 0xfffff000
	s_and_b32 s10, s10, 48
	v_lshlrev_b32_e32 v2, 2, v3
	s_add_i32 s8, s8, 0
	v_or_b32_e32 v7, s21, v107
	v_lshlrev_b32_e32 v8, 4, v99
	v_lshlrev_b32_e32 v5, 1, v106
	v_lshlrev_b32_e32 v6, 3, v106
	s_add_i32 s10, s10, 0
	v_lshl_add_u32 v110, v106, 4, s8
	v_sub_u32_e32 v114, v7, v2
	v_lshlrev_b32_e32 v7, 3, v99
	v_and_b32_e32 v8, 0xc0, v8
	s_movk_i32 s8, 0x100
	s_lshl_b32 s6, s20, 3
	v_lshlrev_b32_e32 v4, 4, v107
	v_and_b32_e32 v5, 32, v5
	v_and_b32_e32 v6, 24, v6
	s_add_i32 s9, s10, s9
	v_and_or_b32 v7, v7, s8, v8
	s_ashr_i32 s7, s6, 31
	v_lshlrev_b32_e32 v0, 3, v3
	v_cmp_gt_u32_e32 vcc, 32, v106
	s_addk_i32 s9, 0x2000
	v_or3_b32 v5, v7, v5, v6
	v_lshl_or_b32 v3, v3, 10, v4
	s_add_i32 s8, 0, 0xc000
	v_cndmask_b32_e64 v108, 0, 1.0, vcc
	v_lshl_add_u32 v109, v106, 6, s9
	s_lshl_b64 s[6:7], s[6:7], 1
	v_or_b32_e32 v111, 64, v106
	v_or_b32_e32 v112, 0x80, v106
	v_or_b32_e32 v113, 0xc0, v106
	v_add_u32_e32 v115, 0, v5
	v_add_u32_e32 v116, s8, v3
	v_lshlrev_b32_e32 v96, 1, v2
	v_lshlrev_b32_e32 v98, 1, v0
	v_and_b32_e32 v148, 7, v106
	v_lshl_add_u32 v148, s20, 3, v148
	v_lshrrev_b32_e32 v147, 3, v106
	v_lshlrev_b32_e32 v110, 4, v148
	v_lshl_add_u32 v110, v147, 10, v110
	v_lshlrev_b32_e32 v109, 6, v148
	v_and_b32_e32 v146, 3, v147
	v_lshl_add_u32 v109, v146, 4, v109
	v_lshrrev_b32_e32 v146, 2, v147
	v_lshl_add_u32 v109, v146, 12, v109
	v_add_u32_e32 v109, 0x2000, v109
	v_or_b32_e32 v111, 64, v148
	v_or_b32_e32 v112, 0x80, v148
	v_or_b32_e32 v113, 0xc0, v148
	v_lshlrev_b32_e32 v146, 4, v147
	v_mov_b32_e32 v147, 0
	s_mov_b32 s20, s2
	s_mov_b32 s22, s2
	s_branch .LBB0_361

; #define LAS __attribute__((address_space(3)))
; DI void swa_wg_unit(bf16_t* act, int b, int hk, int Qb, const float* sinks_l, LAS const float* tabS, LAS unsigned char* lds, int wid, int lane) {
;     const int r = lane & 31, h = lane >> 5;
;     const int Q = Qb * 256, q0 = Q + 32 * wid, qpos = q0 + r;
;     const size_t rowq = (size_t)b * SEQ + qpos;
;     const int t_hi = (Q >> 6) + 3, t_lo = (Q >= 128) ? ((Q - 128) >> 6) : 0;
;     __syncthreads();
;     coop_load_tiles(act + (size_t)b * SEQ * PITCH + C_KC + hk * 64, C_VC - C_KC, t_hi, t_hi - t_lo + 1, lds, wid, lane);
;     __syncthreads();
.LBB0_361:
	s_and_b32 s10, s22, 31
	s_lshl_b32 s26, s10, 8
	s_and_b32 s24, s20, 31
	s_ashr_i32 s8, s22, 6
	s_lshl_b32 s11, s10, 2
	s_add_i32 s12, s26, 0xffffff80
	s_lshl_b32 s23, s24, 8
	s_lshr_b32 s25, s22, 5
	s_ashr_i32 s9, s8, 31
	s_or_b32 s11, s11, 3
	s_ashr_i32 s12, s12, 6
	s_cmp_lg_u32 s10, 0
	s_cselect_b32 s10, s12, 0
	s_sub_i32 s27, s11, s10
	s_cmp_lt_i32 s27, 0
	s_waitcnt lgkmcnt(0)
	s_barrier
	s_cbranch_scc1 .LBB0_376
	s_and_b32 s10, s25, 1
	s_lshl_b32 s12, s10, 7
	s_add_u32 s10, s18, s12
	s_mul_i32 s14, s8, 0x6400000
	s_addc_u32 s11, s19, 0
	s_mul_hi_i32 s13, s8, 0x6400000
	s_add_u32 s10, s10, s14
	s_addc_u32 s11, s11, s13
	v_add_u32_e32 v8, s23, v148
	v_mov_b64_e32 v[6:7], s[10:11]
	v_mad_u64_u32 v[34:35], s[10:11], v8, s31, v[6:7]
	s_or_b32 s10, s14, s12
	v_add_u32_e32 v0, s23, v111
	v_add_u32_e32 v2, s23, v112
	v_add_u32_e32 v4, s23, v113
	s_add_u32 s10, s18, s10
	v_mul_u32_u24_e32 v0, 0x3200, v0
	v_mul_u32_u24_e32 v2, 0x3200, v2
	v_mov_b32_e32 v3, v1
	v_mul_u32_u24_e32 v4, 0x3200, v4
	v_mov_b32_e32 v5, v1
	s_addc_u32 s11, s19, s13
	v_lshl_add_u64 v[36:37], s[10:11], 0, v[0:1]
	v_lshl_add_u64 v[38:39], s[10:11], 0, v[2:3]
	v_lshl_add_u64 v[40:41], s[10:11], 0, v[4:5]
	s_mov_b32 s12, 0
	v_mov_b32_e32 v2, 0
	v_mov_b32_e32 v3, 0
	v_mov_b32_e32 v4, 0
	v_mov_b32_e32 v5, 0
	v_mov_b32_e32 v6, 0
	v_mov_b32_e32 v7, 0
	v_mov_b32_e32 v8, 0
	v_mov_b32_e32 v9, 0
	v_mov_b32_e32 v10, 0
	v_mov_b32_e32 v11, 0
	v_mov_b32_e32 v12, 0
	v_mov_b32_e32 v13, 0
	v_mov_b32_e32 v14, 0
	v_mov_b32_e32 v15, 0
	v_mov_b32_e32 v16, 0
	v_mov_b32_e32 v17, 0
	v_mov_b32_e32 v18, 0
	v_mov_b32_e32 v19, 0
	v_mov_b32_e32 v20, 0
	v_mov_b32_e32 v21, 0
	v_mov_b32_e32 v22, 0
	v_mov_b32_e32 v23, 0
	v_mov_b32_e32 v24, 0
	v_mov_b32_e32 v25, 0
	v_mov_b32_e32 v0, v110
	v_mov_b32_e32 v42, v109
	s_branch .LBB0_364

; #define LAS __attribute__((address_space(3)))
; DI void coop_load_tiles(const bf16_t* kbase, int vdelta, int t_hi, int nt, LAS unsigned char* lds, int wid, int lane) {
; #pragma unroll 1
;     for (int s0 = 0; s0 < nt; s0 += 4) {
;         u32x4 kr[4], vr[4];
; #pragma unroll
;         for (int s = 0; s < 4; ++s) if (s0 + s < nt) { const bf16_t* src = kbase + (size_t)((t_hi - s0 - s) * 64 + lane) * PITCH + 8 * wid; kr[s] = *(const u32x4*)src; vr[s] = *(const u32x4*)(src + vdelta); }
; #pragma unroll
;         for (int s = 0; s < 4; ++s) if (s0 + s < nt) { *(LAS u32x4*)(lds + (s0 + s) * 16384 + wid * 1024 + lane * 16) = kr[s];
;             *(LAS u32x4*)(lds + (s0 + s) * 16384 + 8192 + (wid >> 2) * 4096 + lane * 64 + (wid & 3) * 16) = vr[s]; }
;     }
.LBB0_364:
	v_lshl_add_u64 v[26:27], v[40:41], 0, v[146:147]
	s_mov_b32 s10, 0x3402000
	v_add_co_u32_e32 v26, vcc, s10, v26
	s_cmp_lt_i32 s12, s27
	s_nop 0
	v_addc_co_u32_e32 v27, vcc, 0, v27, vcc
	global_load_dwordx4 v[30:33], v[26:27], off offset:1024
	s_nop 0
	global_load_dwordx4 v[26:29], v[26:27], off offset:1280
	s_cselect_b64 s[10:11], -1, 0
	s_cmp_ge_i32 s12, s27
	s_cbranch_scc1 .LBB0_366
	v_lshl_add_u64 v[2:3], v[38:39], 0, v[146:147]
	v_add_co_u32_e32 v14, vcc, 0x3402000, v2
	s_nop 1
	v_addc_co_u32_e32 v15, vcc, 0, v3, vcc
	global_load_dwordx4 v[2:5], v[14:15], off offset:1024
	s_nop 0
	global_load_dwordx4 v[14:17], v[14:15], off offset:1280
.LBB0_366:
	s_add_i32 s28, s12, 2
	s_cmp_le_i32 s28, s27
	s_cselect_b64 s[12:13], -1, 0
	s_cmp_gt_i32 s28, s27
	s_cbranch_scc1 .LBB0_368
	v_lshl_add_u64 v[6:7], v[36:37], 0, v[146:147]
	v_add_co_u32_e32 v18, vcc, 0x3402000, v6
	s_nop 1
	v_addc_co_u32_e32 v19, vcc, 0, v7, vcc
	global_load_dwordx4 v[6:9], v[18:19], off offset:1024
	s_nop 0
	global_load_dwordx4 v[18:21], v[18:19], off offset:1280

; #define LAS __attribute__((address_space(3)))
; DI void coop_load_tiles(const bf16_t* kbase, int vdelta, int t_hi, int nt, LAS unsigned char* lds, int wid, int lane) {
; #pragma unroll 1
;     for (int s0 = 0; s0 < nt; s0 += 4) {
;         u32x4 kr[4], vr[4];
; #pragma unroll
;         for (int s = 0; s < 4; ++s) if (s0 + s < nt) { const bf16_t* src = kbase + (size_t)((t_hi - s0 - s) * 64 + lane) * PITCH + 8 * wid; kr[s] = *(const u32x4*)src; vr[s] = *(const u32x4*)(src + vdelta); }
; #pragma unroll
;         for (int s = 0; s < 4; ++s) if (s0 + s < nt) { *(LAS u32x4*)(lds + (s0 + s) * 16384 + wid * 1024 + lane * 16) = kr[s];
;             *(LAS u32x4*)(lds + (s0 + s) * 16384 + 8192 + (wid >> 2) * 4096 + lane * 64 + (wid & 3) * 16) = vr[s]; }
;     }
.LBB0_372:
	s_waitcnt vmcnt(3)
	v_lshl_add_u64 v[10:11], v[34:35], 0, v[146:147]
	s_waitcnt vmcnt(2)
	v_add_co_u32_e32 v22, vcc, 0x3402000, v10
	s_nop 1
	v_addc_co_u32_e32 v23, vcc, 0, v11, vcc
	global_load_dwordx4 v[10:13], v[22:23], off offset:1024
	s_nop 0
	global_load_dwordx4 v[22:25], v[22:23], off offset:1280
	s_andn2_b64 vcc, exec, s[10:11]
	s_waitcnt vmcnt(3)
	ds_write_b128 v0, v[30:33]
	s_waitcnt vmcnt(2)
	ds_write_b128 v42, v[26:29]
	s_cbranch_vccnz .LBB0_370

; #define LAS __attribute__((address_space(3)))
; DI void moba_block_phase(bf16_t* act, const unsigned* sel, float* ml, unsigned* qctr, LAS const float* tabM, LAS unsigned char* lds, int tid, int wid, int lane) {
;     volatile LAS unsigned* ctl = (volatile LAS unsigned*)(lds + LDS_CTL);
;     volatile LAS unsigned short* list = (volatile LAS unsigned short*)(lds + 65536);
;     unsigned* gctr = (unsigned*)(LAS unsigned*)(lds + LDS_CTL + 5 * 4);
;     if (tid == 0) ctl[6] = __hip_atomic_fetch_add(qctr, 1u, __ATOMIC_RELAXED, __HIP_MEMORY_SCOPE_AGENT);
;     for (;;) {
;         __syncthreads();
;         const unsigned u = ctl[6];
;         if (u >= 1024u) break;
;         const int j = (int)(u >> 5), bh = (int)(u & 31u), b = bh >> 3, hh = bh & 7;
;         const unsigned* selp = sel + (size_t)bh * SEQ;
;         const int C = (31 - j) * 32, base = (j + 1) * 256 + wid * C;
;         unsigned words[16];
; #pragma unroll
;         for (int k = 0; k < 16; ++k) { const int idx = k * 64 + lane; const unsigned w = selp[base + (idx < C ? idx : 0)]; words[k] = (idx < C) ? w : 0u; }
;         {
;             const bf16_t* kb = act + ((size_t)b * SEQ + j * 256 + lane) * PITCH + C_KB + hh * 64 + 8 * wid;
;             u32x4 kreg[4], vreg[4];
; #pragma unroll
;             for (int t = 0; t < 4; ++t) { kreg[t] = *(const u32x4*)(kb + (size_t)t * 64 * PITCH); vreg[t] = *(const u32x4*)(kb + (size_t)t * 64 * PITCH + (C_VB - C_KB)); }
; #pragma unroll
;             for (int t = 0; t < 4; ++t) { *(LAS u32x4*)(lds + t * 8192 + wid * 1024 + lane * 16) = kreg[t];
;                 *(LAS u32x4*)(lds + 32768 + t * 8192 + (wid >> 2) * 4096 + lane * 64 + (wid & 3) * 16) = vreg[t]; }
;         }
.LBB0_435:
	s_or_b64 exec, exec, s[6:7]
	s_ashr_i32 s38, s14, 6
	s_add_u32 s96, s12, 0x3400000
	s_addc_u32 s97, s13, 0
	s_add_u32 s36, s12, 0x1c400000
	s_addc_u32 s37, s13, 0
	s_add_u32 s92, s12, 0x1c500000
	s_addc_u32 s93, s13, 0
	s_lshl_b32 s6, s38, 10
	s_add_i32 s89, s6, 0
	s_and_b32 s6, s6, 0xfffff000
	v_and_b32_e32 v166, 63, v0
	s_add_i32 s6, s6, 0
	v_lshl_add_u32 v4, v166, 6, s6
	s_lshl_b32 s6, s38, 4
	s_and_b32 s22, s6, 48
	s_lshl_b32 s6, s38, 2
	s_lshl_b32 s94, s38, 3
	s_add_i32 s91, s6, 0
	s_ashr_i32 s95, s94, 31
	s_add_i32 s91, s91, 0x22080
	s_cmp_gt_i32 s38, 0
	s_cselect_b64 s[6:7], -1, 0
	s_cmp_gt_i32 s38, 1
	s_cselect_b64 s[8:9], -1, 0
	s_cmp_gt_i32 s38, 2
	v_lshlrev_b64 v[2:3], v0, -1
	v_lshrrev_b32_e32 v8, 3, v0
	s_cselect_b64 s[10:11], -1, 0
	s_cmp_gt_i32 s38, 3
	v_not_b32_e32 v135, v3
	v_bfe_u32 v3, v0, 2, 4
	v_and_b32_e32 v169, 4, v8
	s_cselect_b64 s[12:13], -1, 0
	s_cmp_gt_i32 s38, 4
	v_not_b32_e32 v134, v2
	v_and_b32_e32 v168, 31, v0
	v_and_b32_e32 v2, 8, v3
	v_bfe_u32 v5, v0, 5, 1
	v_and_or_b32 v3, v3, 3, v169
	v_lshlrev_b32_e32 v8, 1, v0
	v_lshlrev_b32_e32 v0, 3, v0
	s_cselect_b64 s[14:15], -1, 0
	s_cmp_gt_i32 s38, 5
	v_lshlrev_b32_e32 v167, 4, v166
	v_lshl_add_u32 v3, v3, 6, 0
	v_and_b32_e32 v8, 32, v8
	v_and_b32_e32 v0, 24, v0
	s_cselect_b64 s[16:17], -1, 0
	s_cmp_gt_i32 s38, 6
	v_lshl_add_u32 v6, v5, 10, 0
	v_and_b32_e32 v7, 0x1f0, v167
	v_add3_u32 v170, v3, v8, v0
	v_lshlrev_b32_e32 v0, 3, v5
	s_cselect_b64 s[18:19], -1, 0
	v_mov_b32_e32 v118, 0
	s_cmp_gt_i32 s38, 7
	v_cmp_eq_u32_e64 s[42:43], 0, v166
	v_cmp_gt_u32_e64 s[44:45], 32, v166
	v_or_b32_e32 v171, 64, v166
	v_or_b32_e32 v172, 0x80, v166
	v_or_b32_e32 v173, 0xc0, v166
	v_or_b32_e32 v174, 0x100, v166
	v_or_b32_e32 v175, 0x140, v166
	v_or_b32_e32 v176, 0x180, v166
	v_or_b32_e32 v177, 0x1c0, v166
	v_or_b32_e32 v178, 0x200, v166
	v_or_b32_e32 v179, 0x240, v166
	v_or_b32_e32 v180, 0x280, v166
	v_or_b32_e32 v181, 0x2c0, v166
	v_or_b32_e32 v182, 0x300, v166
	v_or_b32_e32 v183, 0x340, v166
	v_or_b32_e32 v184, 0x380, v166
	v_or_b32_e32 v185, 0x3c0, v166
	s_cselect_b64 s[20:21], -1, 0
	v_add_u32_e32 v186, s22, v4
	v_lshlrev_b32_e32 v136, 1, v2
	v_lshlrev_b32_e32 v138, 1, v0
	v_add_u32_e32 v187, v6, v7
	v_mov_b32_e32 v119, v118
	v_mov_b32_e32 v120, v118
	v_mov_b32_e32 v121, v118
	v_mov_b32_e32 v126, v118
	v_mov_b32_e32 v127, v118
	v_mov_b32_e32 v128, v118
	v_mov_b32_e32 v129, v118
	v_mov_b32_e32 v130, v118
	v_mov_b32_e32 v131, v118
	v_mov_b32_e32 v132, v118
	v_mov_b32_e32 v133, v118
	v_mov_b32_e32 v122, v118
	v_mov_b32_e32 v123, v118
	v_mov_b32_e32 v124, v118
	v_mov_b32_e32 v125, v118
	v_and_b32_e32 v238, 7, v166
	v_lshl_add_u32 v238, s38, 3, v238
	v_lshrrev_b32_e32 v239, 3, v166
	v_lshlrev_b32_e32 v240, 4, v239
	v_mov_b32_e32 v241, 0
	v_lshlrev_b32_e32 v186, 6, v238
	v_and_b32_e32 v242, 3, v239
	v_lshl_add_u32 v186, v242, 4, v186
	v_lshrrev_b32_e32 v242, 2, v239
	v_lshl_add_u32 v186, v242, 12, v186
	v_lshlrev_b32_e32 v242, 4, v238
	v_lshl_add_u32 v239, v239, 10, v242
	s_branch .LBB0_438

; #define LAS __attribute__((address_space(3)))
; DI void moba_block_phase(bf16_t* act, const unsigned* sel, float* ml, unsigned* qctr, LAS const float* tabM, LAS unsigned char* lds, int tid, int wid, int lane) {
;     ...
;         const unsigned u = ctl[6];
;         if (u >= 1024u) break;
;         const int j = (int)(u >> 5), bh = (int)(u & 31u), b = bh >> 3, hh = bh & 7;
;         const unsigned* selp = sel + (size_t)bh * SEQ;
;         const int C = (31 - j) * 32, base = (j + 1) * 256 + wid * C;
;         unsigned words[16];
; #pragma unroll
;         for (int k = 0; k < 16; ++k) { const int idx = k * 64 + lane; const unsigned w = selp[base + (idx < C ? idx : 0)]; words[k] = (idx < C) ? w : 0u; }
;         {
;             const bf16_t* kb = act + ((size_t)b * SEQ + j * 256 + lane) * PITCH + C_KB + hh * 64 + 8 * wid;
;             u32x4 kreg[4], vreg[4];
; #pragma unroll
;             for (int t = 0; t < 4; ++t) { kreg[t] = *(const u32x4*)(kb + (size_t)t * 64 * PITCH); vreg[t] = *(const u32x4*)(kb + (size_t)t * 64 * PITCH + (C_VB - C_KB)); }
; #pragma unroll
;             for (int t = 0; t < 4; ++t) { *(LAS u32x4*)(lds + t * 8192 + wid * 1024 + lane * 16) = kreg[t];
;                 *(LAS u32x4*)(lds + 32768 + t * 8192 + (wid >> 2) * 4096 + lane * 64 + (wid & 3) * 16) = vreg[t]; }
;         }
.LBB0_438:
	v_readlane_b32 s24, v250, 28
	s_waitcnt lgkmcnt(0)
	s_barrier
	v_mov_b32_e32 v0, s24
	ds_read_b32 v22, v0
	s_movk_i32 s24, 0x3ff
	s_mov_b64 s[46:47], -1
	s_waitcnt lgkmcnt(0)
	v_cmp_lt_u32_e32 vcc, s24, v22
	v_readfirstlane_b32 s24, v0
	s_cbranch_vccnz .LBB0_529
	v_lshlrev_b32_e32 v0, 15, v22
	v_and_b32_e32 v0, 0xf8000, v0
	v_lshl_add_u64 v[4:5], s[36:37], 0, v[0:1]
	v_not_b32_e32 v0, v22
	v_and_b32_e32 v23, 0x3e0, v0
	v_lshrrev_b32_e32 v19, 5, v22
	v_mul_lo_u32 v2, v23, s38
	v_lshlrev_b32_e32 v144, 8, v19
	v_ashrrev_i32_e32 v3, 31, v2
	v_mov_b32_e32 v145, v1
	v_mov_b32_e32 v254, v23
	v_lshl_add_u64 v[24:25], v[144:145], 0, v[2:3]
	v_cmp_lt_u32_e32 vcc, v166, v254
	s_nop 1
	v_cndmask_b32_e32 v0, 0, v166, vcc
	v_lshl_add_u64 v[252:253], v[0:1], 0, v[24:25]
	v_lshl_add_u64 v[252:253], v[252:253], 2, v[4:5]
	global_load_dword v21, v[252:253], off offset:1024
	v_cmp_lt_u32_e32 vcc, v171, v254
	s_nop 1
	v_cndmask_b32_e32 v0, 0, v171, vcc
	v_lshl_add_u64 v[252:253], v[0:1], 0, v[24:25]
	v_lshl_add_u64 v[252:253], v[252:253], 2, v[4:5]
	global_load_dword v20, v[252:253], off offset:1024
	v_cmp_lt_u32_e32 vcc, v172, v254
	s_nop 1
	v_cndmask_b32_e32 v0, 0, v172, vcc
	v_lshl_add_u64 v[252:253], v[0:1], 0, v[24:25]
	v_lshl_add_u64 v[252:253], v[252:253], 2, v[4:5]
	global_load_dword v18, v[252:253], off offset:1024
	v_cmp_lt_u32_e32 vcc, v173, v254
	s_nop 1
	v_cndmask_b32_e32 v0, 0, v173, vcc
	v_lshl_add_u64 v[252:253], v[0:1], 0, v[24:25]
	v_lshl_add_u64 v[252:253], v[252:253], 2, v[4:5]
	global_load_dword v17, v[252:253], off offset:1024
	v_cmp_lt_u32_e32 vcc, v174, v254
	s_nop 1
	v_cndmask_b32_e32 v0, 0, v174, vcc
	v_lshl_add_u64 v[252:253], v[0:1], 0, v[24:25]
	v_lshl_add_u64 v[252:253], v[252:253], 2, v[4:5]
	global_load_dword v16, v[252:253], off offset:1024
	v_cmp_lt_u32_e32 vcc, v175, v254
	s_nop 1
	v_cndmask_b32_e32 v0, 0, v175, vcc
	v_lshl_add_u64 v[252:253], v[0:1], 0, v[24:25]
	v_lshl_add_u64 v[252:253], v[252:253], 2, v[4:5]
	global_load_dword v14, v[252:253], off offset:1024
	v_cmp_lt_u32_e32 vcc, v176, v254
	s_nop 1
	v_cndmask_b32_e32 v0, 0, v176, vcc
	v_lshl_add_u64 v[252:253], v[0:1], 0, v[24:25]
	v_lshl_add_u64 v[252:253], v[252:253], 2, v[4:5]
	global_load_dword v13, v[252:253], off offset:1024
	v_cmp_lt_u32_e32 vcc, v177, v254
	s_nop 1
	v_cndmask_b32_e32 v0, 0, v177, vcc
	v_lshl_add_u64 v[252:253], v[0:1], 0, v[24:25]
	v_lshl_add_u64 v[252:253], v[252:253], 2, v[4:5]
	global_load_dword v15, v[252:253], off offset:1024
	v_cmp_lt_u32_e32 vcc, v178, v254
	s_nop 1
	v_cndmask_b32_e32 v0, 0, v178, vcc
	v_lshl_add_u64 v[252:253], v[0:1], 0, v[24:25]
	v_lshl_add_u64 v[252:253], v[252:253], 2, v[4:5]
	global_load_dword v12, v[252:253], off offset:1024
	v_cmp_lt_u32_e32 vcc, v179, v254
	s_nop 1
	v_cndmask_b32_e32 v0, 0, v179, vcc
	v_lshl_add_u64 v[252:253], v[0:1], 0, v[24:25]
	v_lshl_add_u64 v[252:253], v[252:253], 2, v[4:5]
	global_load_dword v11, v[252:253], off offset:1024
	v_cmp_lt_u32_e32 vcc, v180, v254
	s_nop 1
	v_cndmask_b32_e32 v0, 0, v180, vcc
	v_lshl_add_u64 v[252:253], v[0:1], 0, v[24:25]
	v_lshl_add_u64 v[252:253], v[252:253], 2, v[4:5]
	global_load_dword v10, v[252:253], off offset:1024
	v_cmp_lt_u32_e32 vcc, v181, v254
	s_nop 1
	v_cndmask_b32_e32 v0, 0, v181, vcc
	v_lshl_add_u64 v[252:253], v[0:1], 0, v[24:25]
	v_lshl_add_u64 v[252:253], v[252:253], 2, v[4:5]
	global_load_dword v9, v[252:253], off offset:1024
	v_cmp_lt_u32_e32 vcc, v182, v254
	s_nop 1
	v_cndmask_b32_e32 v0, 0, v182, vcc
	v_lshl_add_u64 v[252:253], v[0:1], 0, v[24:25]
	v_lshl_add_u64 v[252:253], v[252:253], 2, v[4:5]
	global_load_dword v8, v[252:253], off offset:1024
	v_cmp_lt_u32_e32 vcc, v183, v254
	s_nop 1
	v_cndmask_b32_e32 v0, 0, v183, vcc
	v_lshl_add_u64 v[252:253], v[0:1], 0, v[24:25]
	v_lshl_add_u64 v[252:253], v[252:253], 2, v[4:5]
	global_load_dword v7, v[252:253], off offset:1024
	v_cmp_lt_u32_e32 vcc, v184, v254
	s_nop 1
	v_cndmask_b32_e32 v0, 0, v184, vcc
	v_lshl_add_u64 v[252:253], v[0:1], 0, v[24:25]
	v_lshl_add_u64 v[252:253], v[252:253], 2, v[4:5]
	global_load_dword v6, v[252:253], off offset:1024
	v_cmp_lt_u32_e32 vcc, v185, v254
	s_nop 1
	v_cndmask_b32_e32 v0, 0, v185, vcc
	v_lshl_add_u64 v[252:253], v[0:1], 0, v[24:25]
	v_lshl_add_u64 v[252:253], v[252:253], 2, v[4:5]
	global_load_dword v4, v[252:253], off offset:1024
	s_movk_i32 s24, 0x1900
	v_and_b32_e32 v3, 7, v22
	v_lshlrev_b32_e32 v0, 10, v22
	v_and_b32_e32 v146, 0x6000, v0
	v_or_b32_e32 v0, v146, v144
	v_or_b32_e32 v0, v0, v238
	v_mul_lo_u32 v0, v0, s24
	v_lshl_add_u64 v[22:23], v[0:1], 1, s[96:97]
	v_lshlrev_b32_e32 v0, 7, v3
	v_lshl_add_u64 v[22:23], v[22:23], 0, v[0:1]
	v_lshl_add_u64 v[46:47], v[22:23], 0, v[240:241]
	s_mov_b64 s[24:25], 0x1400
	v_add_co_u32_e32 v22, vcc, s34, v46
	v_lshl_add_u64 v[26:27], v[46:47], 0, s[24:25]
	s_nop 0
	v_addc_co_u32_e32 v23, vcc, 0, v47, vcc
	s_mov_b32 s24, 0xc9000
	v_add_co_u32_e32 v34, vcc, s24, v46
	s_mov_b32 s24, 0x191000
	s_nop 0
	v_addc_co_u32_e32 v35, vcc, 0, v47, vcc
	v_add_co_u32_e32 v42, vcc, s24, v46
	s_mov_b32 s24, 0x259000
	s_nop 0
	v_addc_co_u32_e32 v43, vcc, 0, v47, vcc
	v_add_co_u32_e32 v50, vcc, s24, v46
	global_load_dwordx4 v[22:25], v[22:23], off offset:1024
	s_nop 0
	global_load_dwordx4 v[26:29], v[26:27], off offset:1024
	v_addc_co_u32_e32 v51, vcc, 0, v47, vcc
	global_load_dwordx4 v[30:33], v[34:35], off offset:1024
	s_nop 0
	global_load_dwordx4 v[34:37], v[34:35], off offset:2048
	s_nop 0
	global_load_dwordx4 v[38:41], v[42:43], off offset:1024
	s_nop 0
	global_load_dwordx4 v[42:45], v[42:43], off offset:2048
	s_nop 0
	global_load_dwordx4 v[46:49], v[50:51], off offset:1024
	s_nop 0
	global_load_dwordx4 v[50:53], v[50:51], off offset:2048
	s_waitcnt vmcnt(8)
; #define LAS __attribute__((address_space(3)))
; DI void moba_block_phase(bf16_t* act, const unsigned* sel, float* ml, unsigned* qctr, LAS const float* tabM, LAS unsigned char* lds, int tid, int wid, int lane) {
;     ...
;         for (int k = 0; k < 16; ++k) { const int idx = k * 64 + lane; const unsigned w = selp[base + (idx < C ? idx : 0)]; words[k] = (idx < C) ? w : 0u; }
;         {
;             const bf16_t* kb = act + ((size_t)b * SEQ + j * 256 + lane) * PITCH + C_KB + hh * 64 + 8 * wid;
;             u32x4 kreg[4], vreg[4];
; #pragma unroll
;             for (int t = 0; t < 4; ++t) { kreg[t] = *(const u32x4*)(kb + (size_t)t * 64 * PITCH); vreg[t] = *(const u32x4*)(kb + (size_t)t * 64 * PITCH + (C_VB - C_KB)); }
; #pragma unroll
;             for (int t = 0; t < 4; ++t) { *(LAS u32x4*)(lds + t * 8192 + wid * 1024 + lane * 16) = kreg[t];
;                 *(LAS u32x4*)(lds + 32768 + t * 8192 + (wid >> 2) * 4096 + lane * 64 + (wid & 3) * 16) = vreg[t]; }
;         }
;         int cnt = 0;
; #pragma unroll
;         for (int k = 0; k < 16; ++k) cnt += __popcll(__ballot(((words[k] >> j) & 1u) != 0u));
;         if (lane == 0) ctl[8 + wid] = (unsigned)cnt;
	v_cmp_lt_u32_e32 vcc, v166, v254
	s_nop 1
	v_cndmask_b32_e32 v21, 0, v21, vcc
	v_cmp_lt_u32_e32 vcc, v171, v254
	s_nop 1
	v_cndmask_b32_e32 v20, 0, v20, vcc
	v_cmp_lt_u32_e32 vcc, v172, v254
	s_nop 1
	v_cndmask_b32_e32 v18, 0, v18, vcc
	v_cmp_lt_u32_e32 vcc, v173, v254
	s_nop 1
	v_cndmask_b32_e32 v17, 0, v17, vcc
	v_cmp_lt_u32_e32 vcc, v174, v254
	s_nop 1
	v_cndmask_b32_e32 v16, 0, v16, vcc
	v_cmp_lt_u32_e32 vcc, v175, v254
	s_nop 1
	v_cndmask_b32_e32 v14, 0, v14, vcc
	v_cmp_lt_u32_e32 vcc, v176, v254
	s_nop 1
	v_cndmask_b32_e32 v13, 0, v13, vcc
	v_cmp_lt_u32_e32 vcc, v177, v254
	s_nop 1
	v_cndmask_b32_e32 v15, 0, v15, vcc
	v_cmp_lt_u32_e32 vcc, v178, v254
	s_nop 1
	v_cndmask_b32_e32 v12, 0, v12, vcc
	v_cmp_lt_u32_e32 vcc, v179, v254
	s_nop 1
	v_cndmask_b32_e32 v11, 0, v11, vcc
	v_cmp_lt_u32_e32 vcc, v180, v254
	s_nop 1
	v_cndmask_b32_e32 v10, 0, v10, vcc
	v_cmp_lt_u32_e32 vcc, v181, v254
	s_nop 1
	v_cndmask_b32_e32 v9, 0, v9, vcc
	v_cmp_lt_u32_e32 vcc, v182, v254
	s_nop 1
	v_cndmask_b32_e32 v8, 0, v8, vcc
	v_cmp_lt_u32_e32 vcc, v183, v254
	s_nop 1
	v_cndmask_b32_e32 v7, 0, v7, vcc
	v_cmp_lt_u32_e32 vcc, v184, v254
	s_nop 1
	v_cndmask_b32_e32 v6, 0, v6, vcc
	v_cmp_lt_u32_e32 vcc, v185, v254
	s_nop 1
	v_cndmask_b32_e32 v4, 0, v4, vcc
	v_mov_b32_e32 v0, v239
	s_waitcnt vmcnt(7)
	ds_write_b128 v0, v[22:25]
	s_waitcnt vmcnt(6)
	ds_write_b128 v186, v[26:29] offset:32768
	s_waitcnt vmcnt(5)
	ds_write_b128 v0, v[30:33] offset:8192
	s_waitcnt vmcnt(4)
	ds_write_b128 v186, v[34:37] offset:40960
	s_waitcnt vmcnt(3)
	ds_write_b128 v0, v[38:41] offset:16384
	s_waitcnt vmcnt(2)
	ds_write_b128 v186, v[42:45] offset:49152
	s_waitcnt vmcnt(1)
	ds_write_b128 v0, v[46:49] offset:24576
	s_waitcnt vmcnt(0)
	ds_write_b128 v186, v[50:53] offset:57344
	v_lshlrev_b32_e64 v0, v19, 1
	v_and_b32_e32 v5, v21, v0
	v_cmp_ne_u32_e64 s[74:75], 0, v5
	v_and_b32_e32 v5, v20, v0
	v_cmp_ne_u32_e64 s[72:73], 0, v5
	v_and_b32_e32 v5, v18, v0
	v_cmp_ne_u32_e64 s[70:71], 0, v5
	v_and_b32_e32 v5, v17, v0
	v_cmp_ne_u32_e64 s[68:69], 0, v5
	v_and_b32_e32 v5, v16, v0
	v_cmp_ne_u32_e64 s[66:67], 0, v5
	v_and_b32_e32 v5, v14, v0
	v_cmp_ne_u32_e64 s[64:65], 0, v5
	v_and_b32_e32 v5, v13, v0
	v_cmp_ne_u32_e64 s[62:63], 0, v5
	v_and_b32_e32 v5, v15, v0
	v_cmp_ne_u32_e64 s[60:61], 0, v5
	v_and_b32_e32 v5, v12, v0
	v_cmp_ne_u32_e64 s[58:59], 0, v5
	v_and_b32_e32 v5, v11, v0
	v_cmp_ne_u32_e64 s[56:57], 0, v5
	v_and_b32_e32 v5, v10, v0
	v_cmp_ne_u32_e64 s[54:55], 0, v5
	v_and_b32_e32 v5, v9, v0
	v_cmp_ne_u32_e64 s[52:53], 0, v5
	v_and_b32_e32 v5, v8, v0
	v_cmp_ne_u32_e64 s[50:51], 0, v5
	v_and_b32_e32 v5, v7, v0
	v_cmp_ne_u32_e64 s[48:49], 0, v5
	v_and_b32_e32 v5, v6, v0
	v_and_b32_e32 v0, v4, v0
	v_cmp_ne_u32_e64 s[46:47], 0, v5
	v_cmp_ne_u32_e32 vcc, 0, v0
	s_and_saveexec_b64 s[76:77], s[42:43]
	s_cbranch_execz .LBB0_441
	s_bcnt1_i32_b64 s24, s[74:75]
	s_bcnt1_i32_b64 s25, s[72:73]
	s_add_i32 s24, s25, s24
	s_bcnt1_i32_b64 s25, s[70:71]
	s_add_i32 s24, s24, s25
	s_bcnt1_i32_b64 s25, s[68:69]
	s_add_i32 s24, s24, s25
	s_bcnt1_i32_b64 s25, s[66:67]
	s_add_i32 s24, s24, s25
	s_bcnt1_i32_b64 s25, s[64:65]
	s_add_i32 s24, s24, s25
	s_bcnt1_i32_b64 s25, s[62:63]
	s_add_i32 s24, s24, s25
	s_bcnt1_i32_b64 s25, s[60:61]
	s_add_i32 s24, s24, s25
	s_bcnt1_i32_b64 s25, s[58:59]
	s_add_i32 s24, s24, s25
	s_bcnt1_i32_b64 s25, s[56:57]
	s_add_i32 s24, s24, s25
	s_bcnt1_i32_b64 s25, s[54:55]
	s_add_i32 s24, s24, s25
	s_bcnt1_i32_b64 s25, s[52:53]
	s_add_i32 s24, s24, s25
	s_bcnt1_i32_b64 s25, s[50:51]
	s_add_i32 s24, s24, s25
	s_bcnt1_i32_b64 s25, s[48:49]
	s_add_i32 s24, s24, s25
	s_bcnt1_i32_b64 s25, s[46:47]
	s_add_i32 s24, s24, s25
	s_bcnt1_i32_b64 s25, vcc
	s_add_i32 s24, s24, s25
	v_mov_b32_e32 v0, s91
	v_mov_b32_e32 v5, s24
	ds_write_b32 v0, v5 offset:32
